# stack + MERGE half-unit epilogue fin-specialised; NA band path: accumulator ping-pong copies replaced by MFMA SrcC from old set
# speedup vs baseline: 1.0232x; 1.0020x over previous
.LBB0_777:
	s_cmp_ge_i32 s60, s51
	s_cselect_b64 s[4:5], -1, 0
	s_cmp_lt_i32 s60, s51
	s_cselect_b64 s[26:27], -1, 0
	s_add_i32 s60, s49, s60
	s_cmp_ge_u32 s60, s48
	s_cselect_b64 s[68:69], -1, 0
	s_cmp_lt_u32 s60, s52
	s_cselect_b64 s[70:71], -1, 0
	s_and_b64 s[68:69], s[68:69], s[70:71]
	s_or_b64 s[68:69], s[4:5], s[68:69]
	s_andn2_b64 vcc, exec, s[68:69]
	s_cbranch_vccnz .LBB0_802
	s_and_b64 s[4:5], s[4:5], exec
	s_mul_i32 s5, s53, 0x3400
	v_add_u32_e32 v226, s5, v181
	s_cselect_b32 s4, 0, s60
	s_waitcnt lgkmcnt(0)
	ds_read_b128 v[4:7], v226
	s_sub_i32 s4, s4, s46
	s_lshl_b32 s4, s4, 9
	s_add_i32 s61, s4, 0
	s_lshl_b32 s60, s53, 13
	s_add_i32 s61, s61, 0xfc00
	s_mov_b64 s[4:5], -1
	s_and_b64 vcc, exec, s[26:27]
	v_add_f32_e32 v177, 0x41000000, v227
	v_lshlrev_b32_e32 v243, 2, v190
	s_cbranch_vccz .LBB0_784
	s_waitcnt lgkmcnt(0)
	v_mfma_f32_32x32x16_bf16 v[80:95], v[4:7], v[144:147], 0
	ds_read_b128 v[8:11], v226 offset:32
	ds_read_b128 v[12:15], v226 offset:64
	v_add3_u32 v0, s61, v225, v243
	v_add_u32_e32 v2, 0xf00, v0
	v_add_u32_e32 v96, 0xf48, v0
	v_add_u32_e32 v98, 0xf60, v0
	v_mfma_f32_32x32x16_bf16 v[100:115], v[4:7], v[160:163], 0
	s_waitcnt lgkmcnt(0)
	v_mfma_f32_32x32x16_bf16 v[80:95], v[8:11], v[148:151], v[80:95]
	v_mfma_f32_32x32x16_bf16 v[100:115], v[8:11], v[164:167], v[100:115]
	ds_read_b128 v[8:11], v226 offset:96
	v_mfma_f32_32x32x16_bf16 v[80:95], v[12:15], v[152:155], v[80:95]
	v_mfma_f32_32x32x16_bf16 v[100:115], v[12:15], v[168:171], v[100:115]
	v_add_u32_e32 v12, 0xf28, v0
	v_add_u32_e32 v14, 0xf40, v0
	s_waitcnt lgkmcnt(0)
	v_mfma_f32_32x32x16_bf16 v[80:95], v[8:11], v[156:159], v[80:95]
	v_mfma_f32_32x32x16_bf16 v[100:115], v[8:11], v[172:175], v[100:115]
	v_add_u32_e32 v8, 0xf08, v0
	v_add_u32_e32 v10, 0xf20, v0
	s_nop 9
	v_mov_b32_e32 v102, v191
	ds_read2_b32 v[2:3], v2 offset1:1
	v_add_u32_e32 v103, 16, v102
	ds_read2_b32 v[8:9], v8 offset1:1
	v_cmp_ge_i32_e32 vcc, v190, v102
	v_cmp_lt_i32_e64 s[4:5], v190, v103
	s_and_b64 vcc, vcc, s[4:5]
	s_waitcnt lgkmcnt(0)
	v_fmamk_f32 v2, v80, 0x3e38aa3b, v2
	v_cndmask_b32_e32 v2, v237, v2, vcc
	v_cmp_ge_i32_e32 vcc, v194, v102
	v_cmp_lt_i32_e64 s[4:5], v194, v103
	s_and_b64 vcc, vcc, s[4:5]
	v_fmac_f32_e32 v3, 0x3e38aa3b, v81
	ds_read2_b32 v[10:11], v10 offset1:1
	v_cndmask_b32_e32 v3, v237, v3, vcc
	v_cmp_ge_i32_e32 vcc, v195, v102
	v_cmp_lt_i32_e64 s[4:5], v195, v103
	s_and_b64 vcc, vcc, s[4:5]
	v_fmamk_f32 v8, v82, 0x3e38aa3b, v8
	v_cndmask_b32_e32 v8, v237, v8, vcc
	v_cmp_ge_i32_e32 vcc, v196, v102
	v_cmp_lt_i32_e64 s[4:5], v196, v103
	s_and_b64 vcc, vcc, s[4:5]
	v_fmac_f32_e32 v9, 0x3e38aa3b, v83
	ds_read2_b32 v[12:13], v12 offset1:1
	v_cndmask_b32_e32 v9, v237, v9, vcc
	v_cmp_ge_i32_e32 vcc, v197, v102
	v_cmp_lt_i32_e64 s[4:5], v197, v103
	s_and_b64 vcc, vcc, s[4:5]
	s_waitcnt lgkmcnt(0)
	v_fmamk_f32 v10, v84, 0x3e38aa3b, v10
	v_cndmask_b32_e32 v10, v237, v10, vcc
	v_cmp_ge_i32_e32 vcc, v198, v102
	v_cmp_lt_i32_e64 s[4:5], v198, v103
	s_and_b64 vcc, vcc, s[4:5]
	v_fmac_f32_e32 v11, 0x3e38aa3b, v85
	v_cndmask_b32_e32 v11, v237, v11, vcc
	v_cmp_ge_i32_e32 vcc, v199, v102
	v_cmp_lt_i32_e64 s[4:5], v199, v103
	ds_read2_b32 v[14:15], v14 offset1:1
	s_and_b64 vcc, vcc, s[4:5]
	v_fmamk_f32 v12, v86, 0x3e38aa3b, v12
	v_cndmask_b32_e32 v81, v237, v12, vcc
	v_cmp_ge_i32_e32 vcc, v200, v102
	v_cmp_lt_i32_e64 s[4:5], v200, v103
	s_and_b64 vcc, vcc, s[4:5]
	v_fmac_f32_e32 v13, 0x3e38aa3b, v87
	v_max3_f32 v80, v2, s62, v3
	v_cndmask_b32_e32 v82, v237, v13, vcc
	v_add_u32_e32 v13, 16, v190
	ds_read2_b32 v[96:97], v96 offset1:1
	v_max3_f32 v80, v80, v8, v9
	v_cmp_ge_i32_e32 vcc, v13, v102
	v_cmp_lt_i32_e64 s[4:5], v190, v102
	v_max3_f32 v80, v80, v10, v11
	s_and_b64 vcc, vcc, s[4:5]
	s_waitcnt lgkmcnt(0)
	v_fmamk_f32 v13, v88, 0x3e38aa3b, v14
	v_max3_f32 v12, v80, v81, v82
	v_cndmask_b32_e32 v80, v237, v13, vcc
	v_cmp_ge_i32_e32 vcc, v201, v102
	v_cmp_lt_i32_e64 s[4:5], v201, v103
	s_and_b64 vcc, vcc, s[4:5]
	v_fmac_f32_e32 v15, 0x3e38aa3b, v89
	ds_read2_b32 v[98:99], v98 offset1:1
	v_cndmask_b32_e32 v83, v237, v15, vcc
	v_cmp_ge_i32_e32 vcc, v202, v102
	v_cmp_lt_i32_e64 s[4:5], v202, v103
	s_and_b64 vcc, vcc, s[4:5]
	v_fmamk_f32 v13, v90, 0x3e38aa3b, v96
	v_cndmask_b32_e32 v84, v237, v13, vcc
	v_cmp_ge_i32_e32 vcc, v203, v102
	v_cmp_lt_i32_e64 s[4:5], v203, v103
	v_add_u32_e32 v100, 0xf68, v0
	s_and_b64 vcc, vcc, s[4:5]
	v_fmac_f32_e32 v97, 0x3e38aa3b, v91
	ds_read2_b32 v[100:101], v100 offset1:1
	v_cndmask_b32_e32 v85, v237, v97, vcc
	v_cmp_ge_i32_e32 vcc, v204, v102
	v_cmp_lt_i32_e64 s[4:5], v204, v103
	s_and_b64 vcc, vcc, s[4:5]
	s_waitcnt lgkmcnt(0)
	v_fmamk_f32 v13, v92, 0x3e38aa3b, v98
	v_cndmask_b32_e32 v86, v237, v13, vcc
	v_cmp_ge_i32_e32 vcc, v205, v102
	v_cmp_lt_i32_e64 s[4:5], v205, v103
	s_and_b64 vcc, vcc, s[4:5]
	v_fmac_f32_e32 v99, 0x3e38aa3b, v93
	v_cndmask_b32_e32 v87, v237, v99, vcc
	v_cmp_ge_i32_e32 vcc, v206, v102
	v_cmp_lt_i32_e64 s[4:5], v206, v103
	s_and_b64 vcc, vcc, s[4:5]
	v_fmamk_f32 v13, v94, 0x3e38aa3b, v100
	v_max3_f32 v12, v12, v80, v83
	v_cndmask_b32_e32 v88, v237, v13, vcc
	v_cmp_ge_i32_e32 vcc, v207, v102
	v_cmp_lt_i32_e64 s[4:5], v207, v103
	v_max3_f32 v12, v12, v84, v85
	s_and_b64 vcc, vcc, s[4:5]
	v_fmac_f32_e32 v101, 0x3e38aa3b, v95
	v_max3_f32 v12, v12, v86, v87
	v_cndmask_b32_e32 v89, v237, v101, vcc
	v_max3_f32 v12, v12, v88, v89
	v_mov_b32_e32 v13, v12
	s_nop 1
	v_permlane32_swap_b32_e32 v12, v13
	v_max_f32_e32 v12, v12, v13
	v_cmp_gt_f32_e32 vcc, v12, v177
	s_nop 1
	v_cndmask_b32_e32 v230, v227, v12, vcc
	v_sub_f32_e32 v2, v2, v230
	v_exp_f32_e32 v179, v2
	v_sub_f32_e32 v2, v3, v230
	v_exp_f32_e32 v242, v2
	v_sub_f32_e32 v2, v8, v230
	v_exp_f32_e32 v244, v2
	v_sub_f32_e32 v2, v9, v230
	v_exp_f32_e32 v245, v2
	v_sub_f32_e32 v2, v10, v230
	v_exp_f32_e32 v246, v2
	v_sub_f32_e32 v2, v11, v230
	v_exp_f32_e32 v247, v2
	v_sub_f32_e32 v2, v81, v230
	v_exp_f32_e32 v248, v2
	v_sub_f32_e32 v2, v82, v230
	v_exp_f32_e32 v249, v2
	v_sub_f32_e32 v2, v80, v230
	v_exp_f32_e32 v250, v2
	v_sub_f32_e32 v2, v83, v230
	v_exp_f32_e32 v251, v2
	v_sub_f32_e32 v2, v84, v230
	v_exp_f32_e32 v252, v2
	v_sub_f32_e32 v2, v85, v230
	v_exp_f32_e32 v253, v2
	v_sub_f32_e32 v2, v86, v230
	v_sub_f32_e32 v90, v227, v230
	v_exp_f32_e32 v254, v2
	v_sub_f32_e32 v2, v87, v230
	v_exp_f32_e32 v235, v2
	v_sub_f32_e32 v2, v88, v230
	v_exp_f32_e32 v176, v90
	v_exp_f32_e32 v238, v2
	v_sub_f32_e32 v2, v89, v230
	v_exp_f32_e32 v234, v2
	v_cmp_eq_f32_e32 vcc, 1.0, v176
	s_cmp_eq_u64 vcc, exec
	v_cvt_pk_bf16_f32 v12, v179, v242
	v_cvt_pk_bf16_f32 v13, v244, v245
	v_cvt_pk_bf16_f32 v14, v246, v247
	v_cvt_pk_bf16_f32 v15, v248, v249
	v_cvt_pk_bf16_f32 v8, v250, v251
	v_cvt_pk_bf16_f32 v9, v252, v253
	v_cvt_pk_bf16_f32 v10, v254, v235
	v_cvt_pk_bf16_f32 v11, v238, v234
	s_cbranch_scc1 .LBB0_781
	v_pk_mul_f32 v[30:31], v[30:31], v[176:177] op_sel_hi:[1,0]
	v_pk_mul_f32 v[28:29], v[28:29], v[176:177] op_sel_hi:[1,0]
	v_pk_mul_f32 v[26:27], v[26:27], v[176:177] op_sel_hi:[1,0]
	v_pk_mul_f32 v[24:25], v[24:25], v[176:177] op_sel_hi:[1,0]
	v_pk_mul_f32 v[22:23], v[22:23], v[176:177] op_sel_hi:[1,0]
	v_pk_mul_f32 v[20:21], v[20:21], v[176:177] op_sel_hi:[1,0]
	v_pk_mul_f32 v[18:19], v[18:19], v[176:177] op_sel_hi:[1,0]
	v_pk_mul_f32 v[16:17], v[16:17], v[176:177] op_sel_hi:[1,0]
	v_pk_mul_f32 v[46:47], v[46:47], v[176:177] op_sel_hi:[1,0]
	v_pk_mul_f32 v[44:45], v[44:45], v[176:177] op_sel_hi:[1,0]
	v_pk_mul_f32 v[42:43], v[42:43], v[176:177] op_sel_hi:[1,0]
	v_pk_mul_f32 v[40:41], v[40:41], v[176:177] op_sel_hi:[1,0]
	v_pk_mul_f32 v[38:39], v[38:39], v[176:177] op_sel_hi:[1,0]
	v_pk_mul_f32 v[36:37], v[36:37], v[176:177] op_sel_hi:[1,0]
	v_pk_mul_f32 v[34:35], v[34:35], v[176:177] op_sel_hi:[1,0]
	v_pk_mul_f32 v[32:33], v[32:33], v[176:177] op_sel_hi:[1,0]
.LBB0_781:
	v_mov_b32_e32 v118, v208
	v_add_u32_e32 v2, 0xee0, v0
	v_add_u32_e32 v0, 0xee8, v0
	ds_read2_b32 v[2:3], v2 offset1:1
	ds_read2_b32 v[116:117], v0 offset1:1
	v_add_u32_e32 v0, 16, v118
	v_cmp_ge_i32_e32 vcc, v204, v118
	v_cmp_lt_i32_e64 s[4:5], v204, v0
	s_waitcnt lgkmcnt(0)
	v_fmamk_f32 v2, v112, 0x3e38aa3b, v2
	s_and_b64 vcc, vcc, s[4:5]
	v_cndmask_b32_e32 v2, v237, v2, vcc
	v_cmp_ge_i32_e32 vcc, v205, v118
	v_cmp_lt_i32_e64 s[4:5], v205, v0
	v_fmac_f32_e32 v3, 0x3e38aa3b, v113
	s_and_b64 vcc, vcc, s[4:5]
	v_cndmask_b32_e32 v3, v237, v3, vcc
	v_cmp_ge_i32_e32 vcc, v206, v118
	v_cmp_lt_i32_e64 s[4:5], v206, v0
	v_fmamk_f32 v113, v114, 0x3e38aa3b, v116
	s_and_b64 vcc, vcc, s[4:5]
	v_cndmask_b32_e32 v113, v237, v113, vcc
	v_cmp_ge_i32_e32 vcc, v207, v118
	v_cmp_lt_i32_e64 s[4:5], v207, v0
	v_fmac_f32_e32 v117, 0x3e38aa3b, v115
	s_and_b64 vcc, vcc, s[4:5]
	v_max3_f32 v112, v2, s62, v3
	v_cndmask_b32_e32 v114, v237, v117, vcc
	v_max3_f32 v0, v112, v113, v114
	v_mov_b32_e32 v112, v0
	s_nop 1
	v_permlane32_swap_b32_e32 v0, v112
	v_max_f32_e32 v0, v0, v112
	v_add_f32_e32 v112, 0x41000000, v228
	v_cmp_gt_f32_e32 vcc, v0, v112
	s_nop 1
	v_cndmask_b32_e32 v240, v228, v0, vcc
	v_sub_f32_e32 v112, v228, v240
	v_sub_f32_e32 v0, v2, v240
	v_sub_f32_e32 v2, v3, v240
	v_exp_f32_e32 v229, v2
	v_sub_f32_e32 v2, v113, v240
	v_exp_f32_e32 v178, v112
	v_exp_f32_e32 v241, v2
	v_sub_f32_e32 v2, v114, v240
	v_exp_f32_e32 v0, v0
	v_exp_f32_e32 v239, v2
	v_cmp_eq_f32_e32 vcc, 1.0, v178
	s_cmp_eq_u64 vcc, exec
	v_cvt_pk_bf16_f32 v2, v0, v229
	v_cvt_pk_bf16_f32 v3, v241, v239
	s_cbranch_scc1 .LBB0_783
	v_pk_mul_f32 v[62:63], v[62:63], v[178:179] op_sel_hi:[1,0]
	v_pk_mul_f32 v[60:61], v[60:61], v[178:179] op_sel_hi:[1,0]
	v_pk_mul_f32 v[58:59], v[58:59], v[178:179] op_sel_hi:[1,0]
	v_pk_mul_f32 v[56:57], v[56:57], v[178:179] op_sel_hi:[1,0]
	v_pk_mul_f32 v[54:55], v[54:55], v[178:179] op_sel_hi:[1,0]
	v_pk_mul_f32 v[52:53], v[52:53], v[178:179] op_sel_hi:[1,0]
	v_pk_mul_f32 v[50:51], v[50:51], v[178:179] op_sel_hi:[1,0]
	v_pk_mul_f32 v[48:49], v[48:49], v[178:179] op_sel_hi:[1,0]
	v_pk_mul_f32 v[78:79], v[78:79], v[178:179] op_sel_hi:[1,0]
	v_pk_mul_f32 v[76:77], v[76:77], v[178:179] op_sel_hi:[1,0]
	v_pk_mul_f32 v[74:75], v[74:75], v[178:179] op_sel_hi:[1,0]
	v_pk_mul_f32 v[72:73], v[72:73], v[178:179] op_sel_hi:[1,0]
	v_pk_mul_f32 v[70:71], v[70:71], v[178:179] op_sel_hi:[1,0]
	v_pk_mul_f32 v[68:69], v[68:69], v[178:179] op_sel_hi:[1,0]
	v_pk_mul_f32 v[66:67], v[66:67], v[178:179] op_sel_hi:[1,0]
	v_pk_mul_f32 v[64:65], v[64:65], v[178:179] op_sel_hi:[1,0]
.LBB0_783:
	v_add_f32_e32 v0, v0, v229
	v_add_f32_e32 v229, v241, v239
	v_add_f32_e32 v241, v229, v0
	v_fmac_f32_e32 v241, v192, v178
	v_add_f32_e32 v178, v179, v242
	v_add_f32_e32 v179, v244, v245
	v_add_f32_e32 v178, v179, v178
	v_add_f32_e32 v179, v246, v247
	v_add_f32_e32 v178, v179, v178
	v_add_f32_e32 v179, v248, v249
	v_add_f32_e32 v178, v179, v178
	v_add_f32_e32 v179, v250, v251
	v_add_f32_e32 v178, v179, v178
	v_add_f32_e32 v179, v252, v253
	v_add_f32_e32 v178, v179, v178
	v_add_f32_e32 v179, v254, v235
	v_add_f32_e32 v178, v179, v178
	v_add_f32_e32 v179, v238, v234
	v_add_f32_e32 v242, v179, v178
	v_fmac_f32_e32 v242, v193, v176
	v_add_u32_e32 v176, s60, v183
	ds_read_b64_tr_b16 v[244:245], v176 offset:39936
	ds_read_b64_tr_b16 v[246:247], v176 offset:40448
	ds_read_b64_tr_b16 v[248:249], v176 offset:44032
	ds_read_b64_tr_b16 v[250:251], v176 offset:44544
	s_waitcnt lgkmcnt(2)
	v_mfma_f32_32x32x16_bf16 v[80:95], v[244:247], v[12:15], v[16:31]
	v_mov_b32_e32 v0, v1
	s_mov_b64 s[4:5], 0
	s_waitcnt lgkmcnt(0)
	v_mfma_f32_32x32x16_bf16 v[96:111], v[248:251], v[12:15], v[32:47]
	ds_read_b64_tr_b16 v[12:13], v176 offset:40960
	ds_read_b64_tr_b16 v[14:15], v176 offset:41472
	ds_read_b64_tr_b16 v[244:245], v176 offset:45056
	ds_read_b64_tr_b16 v[246:247], v176 offset:45568
	s_waitcnt lgkmcnt(2)
	v_mfma_f32_32x32x16_bf16 v[80:95], v[12:15], v[8:11], v[80:95]
	s_waitcnt lgkmcnt(0)
	v_mfma_f32_32x32x16_bf16 v[96:111], v[244:247], v[8:11], v[96:111]
	v_mfma_f32_32x32x16_bf16 v[112:127], v[12:15], v[0:3], v[48:63]
	v_mfma_f32_32x32x16_bf16 v[128:143], v[244:247], v[0:3], v[64:79]

.LBB0_790:
	ds_read_b128 v[176:179], v226 offset:4608
	s_mov_b64 s[4:5], -1
	s_andn2_b64 vcc, exec, s[26:27]
	v_add_f32_e32 v244, 0x41000000, v230
	s_cbranch_vccnz .LBB0_796
	s_waitcnt lgkmcnt(0)
	v_mfma_f32_32x32x16_bf16 v[2:17], v[176:179], v[144:147], 0
	ds_read_b128 v[18:21], v226 offset:4640
	ds_read_b128 v[22:25], v226 offset:4672
	v_mov_b32_e32 v0, v191
	v_mfma_f32_32x32x16_bf16 v[48:63], v[176:179], v[160:163], 0
	s_waitcnt lgkmcnt(0)
	v_mfma_f32_32x32x16_bf16 v[2:17], v[18:21], v[148:151], v[2:17]
	v_mfma_f32_32x32x16_bf16 v[48:63], v[18:21], v[164:167], v[48:63]
	ds_read_b128 v[18:21], v226 offset:4704
	s_nop 0
	v_cmp_ge_i32_e32 vcc, v209, v0
	v_mfma_f32_32x32x16_bf16 v[2:17], v[22:25], v[152:155], v[2:17]
	s_waitcnt lgkmcnt(0)
	v_mfma_f32_32x32x16_bf16 v[2:17], v[18:21], v[156:159], v[2:17]
	v_mfma_f32_32x32x16_bf16 v[48:63], v[22:25], v[168:171], v[48:63]
	s_nop 10
	v_add3_u32 v6, s61, v225, v243
	v_add_u32_e32 v7, 0xf80, v6
	ds_read2_b32 v[8:9], v7 offset1:1
	v_add_u32_e32 v7, 0xf88, v6
	ds_read2_b32 v[10:11], v7 offset1:1
	v_add_u32_e32 v7, 16, v0
	v_cmp_lt_i32_e64 s[4:5], v209, v7
	s_and_b64 vcc, vcc, s[4:5]
	s_waitcnt lgkmcnt(0)
	v_fmamk_f32 v2, v2, 0x3e38aa3b, v8
	v_cndmask_b32_e32 v2, v237, v2, vcc
	v_cmp_ge_i32_e32 vcc, v210, v0
	v_cmp_lt_i32_e64 s[4:5], v210, v7
	s_and_b64 vcc, vcc, s[4:5]
	v_fmac_f32_e32 v9, 0x3e38aa3b, v3
	v_cndmask_b32_e32 v3, v237, v9, vcc
	v_cmp_ge_i32_e32 vcc, v211, v0
	v_cmp_lt_i32_e64 s[4:5], v211, v7
	s_and_b64 vcc, vcc, s[4:5]
	v_fmamk_f32 v4, v4, 0x3e38aa3b, v10
	v_cndmask_b32_e32 v4, v237, v4, vcc
	v_cmp_ge_i32_e32 vcc, v212, v0
	v_cmp_lt_i32_e64 s[4:5], v212, v7
	s_and_b64 vcc, vcc, s[4:5]
	v_fmac_f32_e32 v11, 0x3e38aa3b, v5
	v_max3_f32 v8, v2, s62, v3
	v_cndmask_b32_e32 v0, v237, v11, vcc
	v_max3_f32 v5, v8, v4, v0
	v_mov_b32_e32 v7, v5
	s_nop 1
	v_permlane32_swap_b32_e32 v5, v7
	v_max_f32_e32 v5, v5, v7
	v_cmp_gt_f32_e32 vcc, v5, v244
	v_mfma_f32_32x32x16_bf16 v[48:63], v[18:21], v[172:175], v[48:63]
	s_nop 0
	v_cndmask_b32_e32 v227, v230, v5, vcc
	v_sub_f32_e32 v7, v230, v227
	v_sub_f32_e32 v0, v0, v227
	v_sub_f32_e32 v2, v2, v227
	v_exp_f32_e32 v193, v0
	v_exp_f32_e32 v0, v7
	v_exp_f32_e32 v5, v2
	v_sub_f32_e32 v2, v3, v227
	v_sub_f32_e32 v3, v4, v227
	v_exp_f32_e32 v14, v2
	v_exp_f32_e32 v15, v3
	v_cmp_eq_f32_e32 vcc, 1.0, v0
	s_cmp_eq_u64 vcc, exec
	v_cvt_pk_bf16_f32 v2, v5, v14
	v_cvt_pk_bf16_f32 v3, v15, v193
	s_cbranch_scc1 .LBB0_793
	v_pk_mul_f32 v[94:95], v[94:95], v[0:1] op_sel_hi:[1,0]
	v_pk_mul_f32 v[92:93], v[92:93], v[0:1] op_sel_hi:[1,0]
	v_pk_mul_f32 v[90:91], v[90:91], v[0:1] op_sel_hi:[1,0]
	v_pk_mul_f32 v[88:89], v[88:89], v[0:1] op_sel_hi:[1,0]
	v_pk_mul_f32 v[86:87], v[86:87], v[0:1] op_sel_hi:[1,0]
	v_pk_mul_f32 v[84:85], v[84:85], v[0:1] op_sel_hi:[1,0]
	v_pk_mul_f32 v[82:83], v[82:83], v[0:1] op_sel_hi:[1,0]
	v_pk_mul_f32 v[80:81], v[80:81], v[0:1] op_sel_hi:[1,0]
	v_pk_mul_f32 v[110:111], v[110:111], v[0:1] op_sel_hi:[1,0]
	v_pk_mul_f32 v[108:109], v[108:109], v[0:1] op_sel_hi:[1,0]
	v_pk_mul_f32 v[106:107], v[106:107], v[0:1] op_sel_hi:[1,0]
	v_pk_mul_f32 v[104:105], v[104:105], v[0:1] op_sel_hi:[1,0]
	v_pk_mul_f32 v[102:103], v[102:103], v[0:1] op_sel_hi:[1,0]
	v_pk_mul_f32 v[100:101], v[100:101], v[0:1] op_sel_hi:[1,0]
	v_pk_mul_f32 v[98:99], v[98:99], v[0:1] op_sel_hi:[1,0]
	v_pk_mul_f32 v[96:97], v[96:97], v[0:1] op_sel_hi:[1,0]
.LBB0_793:
	v_mov_b32_e32 v4, v208
	v_add_u32_e32 v7, 0xf00, v6
	v_add_u32_e32 v10, 0xf08, v6
	v_add_u32_e32 v12, 0xf20, v6
	v_add_u32_e32 v64, 0xf28, v6
	ds_read2_b32 v[8:9], v7 offset1:1
	ds_read2_b32 v[10:11], v10 offset1:1
	ds_read2_b32 v[12:13], v12 offset1:1
	ds_read2_b32 v[64:65], v64 offset1:1
	v_add_u32_e32 v72, 16, v4
	v_cmp_ge_i32_e32 vcc, v209, v4
	v_cmp_lt_i32_e64 s[4:5], v209, v72
	s_waitcnt lgkmcnt(0)
	v_fmamk_f32 v8, v48, 0x3e38aa3b, v8
	s_and_b64 vcc, vcc, s[4:5]
	v_cndmask_b32_e32 v8, v237, v8, vcc
	v_cmp_ge_i32_e32 vcc, v210, v4
	v_cmp_lt_i32_e64 s[4:5], v210, v72
	v_fmac_f32_e32 v9, 0x3e38aa3b, v49
	s_and_b64 vcc, vcc, s[4:5]
	v_cndmask_b32_e32 v9, v237, v9, vcc
	v_cmp_ge_i32_e32 vcc, v211, v4
	v_cmp_lt_i32_e64 s[4:5], v211, v72
	v_fmamk_f32 v10, v50, 0x3e38aa3b, v10
	s_and_b64 vcc, vcc, s[4:5]
	v_cndmask_b32_e32 v49, v237, v10, vcc
	v_cmp_ge_i32_e32 vcc, v212, v4
	v_cmp_lt_i32_e64 s[4:5], v212, v72
	v_fmac_f32_e32 v11, 0x3e38aa3b, v51
	s_and_b64 vcc, vcc, s[4:5]
	v_cndmask_b32_e32 v11, v237, v11, vcc
	v_cmp_ge_i32_e32 vcc, v213, v4
	v_cmp_lt_i32_e64 s[4:5], v213, v72
	v_fmamk_f32 v12, v52, 0x3e38aa3b, v12
	s_and_b64 vcc, vcc, s[4:5]
	v_cndmask_b32_e32 v12, v237, v12, vcc
	v_cmp_ge_i32_e32 vcc, v214, v4
	v_cmp_lt_i32_e64 s[4:5], v214, v72
	v_fmac_f32_e32 v13, 0x3e38aa3b, v53
	s_and_b64 vcc, vcc, s[4:5]
	v_max3_f32 v48, v8, s62, v9
	v_cndmask_b32_e32 v13, v237, v13, vcc
	v_cmp_ge_i32_e32 vcc, v215, v4
	v_cmp_lt_i32_e64 s[4:5], v215, v72
	v_max3_f32 v10, v48, v49, v11
	v_fmamk_f32 v48, v54, 0x3e38aa3b, v64
	s_and_b64 vcc, vcc, s[4:5]
	v_add_u32_e32 v7, 0xf40, v6
	v_add_u32_e32 v66, 0xf48, v6
	v_add_u32_e32 v68, 0xf60, v6
	v_add_u32_e32 v70, 0xf68, v6
	v_cndmask_b32_e32 v48, v237, v48, vcc
	v_cmp_ge_i32_e32 vcc, v216, v4
	v_cmp_lt_i32_e64 s[4:5], v216, v72
	ds_read2_b32 v[6:7], v7 offset1:1
	ds_read2_b32 v[66:67], v66 offset1:1
	ds_read2_b32 v[68:69], v68 offset1:1
	ds_read2_b32 v[70:71], v70 offset1:1
	v_fmac_f32_e32 v65, 0x3e38aa3b, v55
	s_and_b64 vcc, vcc, s[4:5]
	v_cndmask_b32_e32 v50, v237, v65, vcc
	v_cmp_ge_i32_e32 vcc, v217, v4
	v_cmp_lt_i32_e64 s[4:5], v217, v72
	s_waitcnt lgkmcnt(0)
	v_fmamk_f32 v6, v56, 0x3e38aa3b, v6
	s_and_b64 vcc, vcc, s[4:5]
	v_cndmask_b32_e32 v6, v237, v6, vcc
	v_cmp_ge_i32_e32 vcc, v218, v4
	v_cmp_lt_i32_e64 s[4:5], v218, v72
	v_fmac_f32_e32 v7, 0x3e38aa3b, v57
	s_and_b64 vcc, vcc, s[4:5]
	v_cndmask_b32_e32 v7, v237, v7, vcc
	v_cmp_ge_i32_e32 vcc, v219, v4
	v_cmp_lt_i32_e64 s[4:5], v219, v72
	v_fmamk_f32 v51, v58, 0x3e38aa3b, v66
	s_and_b64 vcc, vcc, s[4:5]
	v_cndmask_b32_e32 v51, v237, v51, vcc
	v_cmp_ge_i32_e32 vcc, v220, v4
	v_cmp_lt_i32_e64 s[4:5], v220, v72
	v_fmac_f32_e32 v67, 0x3e38aa3b, v59
	s_and_b64 vcc, vcc, s[4:5]
	v_cndmask_b32_e32 v52, v237, v67, vcc
	v_cmp_ge_i32_e32 vcc, v221, v4
	v_cmp_lt_i32_e64 s[4:5], v221, v72
	v_fmamk_f32 v53, v60, 0x3e38aa3b, v68
	s_and_b64 vcc, vcc, s[4:5]
	v_cndmask_b32_e32 v53, v237, v53, vcc
	v_cmp_ge_i32_e32 vcc, v222, v4
	v_cmp_lt_i32_e64 s[4:5], v222, v72
	v_fmac_f32_e32 v69, 0x3e38aa3b, v61
	s_and_b64 vcc, vcc, s[4:5]
	v_max3_f32 v10, v10, v12, v13
	v_cndmask_b32_e32 v54, v237, v69, vcc
	v_cmp_ge_i32_e32 vcc, v223, v4
	v_cmp_lt_i32_e64 s[4:5], v223, v72
	v_max3_f32 v10, v10, v48, v50
	v_fmamk_f32 v55, v62, 0x3e38aa3b, v70
	s_and_b64 vcc, vcc, s[4:5]
	v_max3_f32 v10, v10, v6, v7
	v_cndmask_b32_e32 v55, v237, v55, vcc
	v_cmp_ge_i32_e32 vcc, v224, v4
	v_cmp_lt_i32_e64 s[4:5], v224, v72
	v_max3_f32 v10, v10, v51, v52
	v_fmac_f32_e32 v71, 0x3e38aa3b, v63
	s_and_b64 vcc, vcc, s[4:5]
	v_max3_f32 v10, v10, v53, v54
	v_cndmask_b32_e32 v4, v237, v71, vcc
	v_max3_f32 v10, v10, v55, v4
	v_mov_b32_e32 v56, v10
	s_nop 1
	v_permlane32_swap_b32_e32 v10, v56
	v_max_f32_e32 v10, v10, v56
	v_add_f32_e32 v56, 0x41000000, v240
	v_cmp_gt_f32_e32 vcc, v10, v56
	s_nop 1
	v_cndmask_b32_e32 v228, v240, v10, vcc
	v_sub_f32_e32 v8, v8, v228
	v_exp_f32_e32 v192, v8
	v_sub_f32_e32 v8, v9, v228
	v_sub_f32_e32 v9, v49, v228
	v_sub_f32_e32 v6, v6, v228
	v_exp_f32_e32 v235, v9
	v_sub_f32_e32 v9, v11, v228
	v_exp_f32_e32 v248, v6
	v_sub_f32_e32 v6, v7, v228
	v_sub_f32_e32 v7, v51, v228
	v_exp_f32_e32 v238, v9
	v_sub_f32_e32 v9, v12, v228
	v_exp_f32_e32 v250, v7
	v_sub_f32_e32 v7, v52, v228
	v_exp_f32_e32 v234, v8
	v_sub_f32_e32 v8, v240, v228
	v_exp_f32_e32 v243, v9
	v_sub_f32_e32 v9, v13, v228
	v_exp_f32_e32 v251, v7
	v_sub_f32_e32 v7, v53, v228
	v_sub_f32_e32 v4, v4, v228
	v_exp_f32_e32 v245, v9
	v_sub_f32_e32 v9, v48, v228
	v_exp_f32_e32 v252, v7
	v_sub_f32_e32 v7, v54, v228
	v_exp_f32_e32 v229, v4
	v_exp_f32_e32 v4, v8
	v_exp_f32_e32 v246, v9
	v_sub_f32_e32 v9, v50, v228
	v_exp_f32_e32 v253, v7
	v_sub_f32_e32 v7, v55, v228
	v_exp_f32_e32 v247, v9
	v_exp_f32_e32 v249, v6
	v_exp_f32_e32 v254, v7
	v_cmp_eq_f32_e32 vcc, 1.0, v4
	s_cmp_eq_u64 vcc, exec
	v_cvt_pk_bf16_f32 v10, v192, v234
	v_cvt_pk_bf16_f32 v11, v235, v238
	v_cvt_pk_bf16_f32 v12, v243, v245
	v_cvt_pk_bf16_f32 v13, v246, v247
	v_cvt_pk_bf16_f32 v6, v248, v249
	v_cvt_pk_bf16_f32 v7, v250, v251
	v_cvt_pk_bf16_f32 v8, v252, v253
	v_cvt_pk_bf16_f32 v9, v254, v229
	s_cbranch_scc1 .LBB0_795
	v_pk_mul_f32 v[126:127], v[126:127], v[4:5] op_sel_hi:[1,0]
	v_pk_mul_f32 v[124:125], v[124:125], v[4:5] op_sel_hi:[1,0]
	v_pk_mul_f32 v[122:123], v[122:123], v[4:5] op_sel_hi:[1,0]
	v_pk_mul_f32 v[120:121], v[120:121], v[4:5] op_sel_hi:[1,0]
	v_pk_mul_f32 v[118:119], v[118:119], v[4:5] op_sel_hi:[1,0]
	v_pk_mul_f32 v[116:117], v[116:117], v[4:5] op_sel_hi:[1,0]
	v_pk_mul_f32 v[114:115], v[114:115], v[4:5] op_sel_hi:[1,0]
	v_pk_mul_f32 v[112:113], v[112:113], v[4:5] op_sel_hi:[1,0]
	v_pk_mul_f32 v[142:143], v[142:143], v[4:5] op_sel_hi:[1,0]
	v_pk_mul_f32 v[140:141], v[140:141], v[4:5] op_sel_hi:[1,0]
	v_pk_mul_f32 v[138:139], v[138:139], v[4:5] op_sel_hi:[1,0]
	v_pk_mul_f32 v[136:137], v[136:137], v[4:5] op_sel_hi:[1,0]
	v_pk_mul_f32 v[134:135], v[134:135], v[4:5] op_sel_hi:[1,0]
	v_pk_mul_f32 v[132:133], v[132:133], v[4:5] op_sel_hi:[1,0]
	v_pk_mul_f32 v[130:131], v[130:131], v[4:5] op_sel_hi:[1,0]
	v_pk_mul_f32 v[128:129], v[128:129], v[4:5] op_sel_hi:[1,0]
.LBB0_795:
	v_add_f32_e32 v192, v192, v234
	v_add_f32_e32 v234, v235, v238
	v_add_f32_e32 v192, v234, v192
	v_add_f32_e32 v234, v243, v245
	v_add_f32_e32 v192, v234, v192
	v_add_f32_e32 v234, v246, v247
	v_add_f32_e32 v192, v234, v192
	v_add_f32_e32 v234, v248, v249
	v_add_f32_e32 v192, v234, v192
	v_add_f32_e32 v234, v250, v251
	v_add_f32_e32 v192, v234, v192
	v_add_f32_e32 v234, v252, v253
	v_add_f32_e32 v192, v234, v192
	v_add_f32_e32 v229, v254, v229
	v_add_f32_e32 v192, v229, v192
	v_fmac_f32_e32 v192, v241, v4
	v_add_f32_e32 v4, v5, v14
	v_add_f32_e32 v5, v15, v193
	v_add_f32_e32 v193, v5, v4
	v_fmac_f32_e32 v193, v242, v0
	v_add_u32_e32 v0, s60, v183
	ds_read_b64_tr_b16 v[246:247], v0 offset:41984
	ds_read_b64_tr_b16 v[248:249], v0 offset:42496
	ds_read_b64_tr_b16 v[250:251], v0 offset:46080
	ds_read_b64_tr_b16 v[252:253], v0 offset:46592
	s_waitcnt lgkmcnt(2)
	v_mfma_f32_32x32x16_bf16 v[48:63], v[246:249], v[10:13], v[112:127]
	v_mov_b32_e32 v4, v1
	v_mov_b32_e32 v5, v1
	s_mov_b64 s[4:5], 0
	s_waitcnt lgkmcnt(0)
	v_mfma_f32_32x32x16_bf16 v[64:79], v[250:253], v[10:13], v[128:143]
	v_mfma_f32_32x32x16_bf16 v[16:31], v[246:249], v[2:5], v[80:95]
	v_mfma_f32_32x32x16_bf16 v[32:47], v[250:253], v[2:5], v[96:111]
	ds_read_b64_tr_b16 v[2:3], v0 offset:43008
	ds_read_b64_tr_b16 v[4:5], v0 offset:43520
	ds_read_b64_tr_b16 v[10:11], v0 offset:47104
	ds_read_b64_tr_b16 v[12:13], v0 offset:47616
	s_waitcnt lgkmcnt(2)
	v_mfma_f32_32x32x16_bf16 v[48:63], v[2:5], v[6:9], v[48:63]
	s_waitcnt lgkmcnt(0)
	v_mfma_f32_32x32x16_bf16 v[64:79], v[10:13], v[6:9], v[64:79]

.LBB0_1134:
	s_lshl_b32 s28, s43, 10
	s_add_i32 s13, s28, 0x400
	s_cmp_eq_u32 s43, 2
	s_cselect_b64 s[20:21], -1, 0
	s_and_b64 s[4:5], s[20:21], exec
	v_mbcnt_lo_u32_b32 v80, -1, 0
	v_mbcnt_hi_u32_b32 v80, -1, v80
	s_cselect_b32 s4, 0x800, s13
	s_lshl_b32 s13, s48, 6
	s_lshl_b32 s5, s49, 8
	s_and_b32 s13, s13, 0x7fffff80
	s_add_i32 s13, s13, s5
	v_and_or_b32 v92, v80, 15, s33
	v_ashrrev_i32_e32 v80, 1, v80
	s_lshl_b32 s26, s4, 1
	s_lshl_b32 s4, s24, 8
	v_and_b32_e32 v82, -8, v80
	v_add_u32_e32 v84, s13, v92
	v_mov_b64_e32 v[80:81], s[8:9]
	s_or_b32 s23, s4, s40
	v_mad_i64_i32 v[80:81], s[4:5], v84, s85, v[80:81]
	v_lshl_add_u64 v[88:89], v[80:81], 0, s[88:89]
	v_add_u32_e32 v80, s23, v82
	s_lshl_b32 s86, s43, 11
	v_ashrrev_i32_e32 v81, 31, v80
	s_mov_b32 s27, s87
	v_lshl_add_u64 v[86:87], v[88:89], 0, s[86:87]
	v_lshlrev_b64 v[82:83], 1, v[80:81]
	v_lshl_add_u64 v[88:89], v[88:89], 0, s[26:27]
	v_lshl_add_u64 v[86:87], v[86:87], 0, v[82:83]
	v_lshl_add_u64 v[88:89], v[88:89], 0, v[82:83]
	s_cmp_lg_u64 s[20:21], 0
	s_cbranch_scc1 .Lmrg_fin_B
	global_load_dwordx4 v[94:97], v[86:87], off
	global_load_dwordx4 v[98:101], v[88:89], off
	global_load_dwordx4 v[176:179], v[86:87], off offset:256
	global_load_dwordx4 v[180:183], v[88:89], off offset:256
	v_ashrrev_i32_e32 v85, 31, v84
	v_lshlrev_b64 v[84:85], 11, v[84:85]
	s_cmp_lg_u32 s43, 2
	v_lshl_add_u64 v[84:85], s[10:11], 0, v[84:85]
	s_waitcnt vmcnt(2)
	v_lshlrev_b32_e32 v93, 16, v94
	v_and_b32_e32 v102, 0xffff0000, v94
	v_lshlrev_b32_e32 v103, 16, v95
	v_and_b32_e32 v104, 0xffff0000, v95
	v_lshlrev_b32_e32 v94, 16, v98
	v_and_b32_e32 v95, 0xffff0000, v98
	v_lshlrev_b32_e32 v98, 16, v99
	v_and_b32_e32 v99, 0xffff0000, v99
	v_lshlrev_b32_e32 v105, 16, v96
	v_and_b32_e32 v106, 0xffff0000, v96
	v_lshlrev_b32_e32 v107, 16, v97
	v_and_b32_e32 v108, 0xffff0000, v97
	v_lshlrev_b32_e32 v96, 16, v100
	v_and_b32_e32 v97, 0xffff0000, v100
	v_lshlrev_b32_e32 v100, 16, v101
	v_and_b32_e32 v101, 0xffff0000, v101
	v_max_f32_e32 v94, 0x1e3ce508, v94
	v_max_f32_e32 v95, 0x1e3ce508, v95
	v_max_f32_e32 v98, 0x1e3ce508, v98
	v_max_f32_e32 v99, 0x1e3ce508, v99
	v_max_f32_e32 v96, 0x1e3ce508, v96
	v_max_f32_e32 v97, 0x1e3ce508, v97
	v_max_f32_e32 v100, 0x1e3ce508, v100
	v_max_f32_e32 v101, 0x1e3ce508, v101
	v_rcp_f32_e32 v94, v94
	v_rcp_f32_e32 v95, v95
	v_rcp_f32_e32 v98, v98
	v_rcp_f32_e32 v99, v99
	v_rcp_f32_e32 v96, v96
	v_rcp_f32_e32 v97, v97
	v_rcp_f32_e32 v100, v100
	v_rcp_f32_e32 v101, v101
	v_mov_b32_e32 v109, v96
	v_mov_b32_e32 v110, v97
	v_mul_f32_e32 v94, v94, v93
	v_mul_f32_e32 v95, v95, v102
	v_mul_f32_e32 v96, v98, v103
	v_mul_f32_e32 v97, v99, v104
	v_mul_f32_e32 v98, v109, v105
	v_mul_f32_e32 v99, v110, v106
	v_mul_f32_e32 v100, v100, v107
	v_mul_f32_e32 v101, v101, v108
	v_pk_mul_f32 v[64:65], v[64:65], v[96:97]
	v_pk_mul_f32 v[62:63], v[62:63], v[94:95]
	v_pk_mul_f32 v[60:61], v[60:61], v[100:101]
	v_pk_mul_f32 v[58:59], v[58:59], v[98:99]
	s_waitcnt vmcnt(0)
	s_cbranch_scc1 .LBB0_1136
	v_lshl_add_u64 v[98:99], v[80:81], 1, v[84:85]
	v_cvt_pk_bf16_f32 v94, v62, v63
	v_cvt_pk_bf16_f32 v95, v64, v65
	v_cvt_pk_bf16_f32 v96, v58, v59
	v_cvt_pk_bf16_f32 v97, v60, v61
	global_store_dwordx4 v[98:99], v[94:97], off
.LBB0_1136:
	v_cndmask_b32_e64 v93, 0, 1, s[20:21]
	v_cmp_ne_u32_e64 s[4:5], 1, v93
	s_andn2_b64 vcc, exec, s[20:21]
	v_lshlrev_b32_e32 v93, 16, v176
	v_lshlrev_b32_e32 v99, 16, v180
	v_and_b32_e32 v180, 0xffff0000, v180
	v_lshlrev_b32_e32 v100, 16, v181
	v_and_b32_e32 v181, 0xffff0000, v181
	v_lshlrev_b32_e32 v103, 16, v182
	v_and_b32_e32 v182, 0xffff0000, v182
	v_lshlrev_b32_e32 v104, 16, v183
	v_and_b32_e32 v183, 0xffff0000, v183
	v_max_f32_e32 v99, 0x1e3ce508, v99
	v_max_f32_e32 v180, 0x1e3ce508, v180
	v_max_f32_e32 v100, 0x1e3ce508, v100
	v_max_f32_e32 v181, 0x1e3ce508, v181
	v_max_f32_e32 v103, 0x1e3ce508, v103
	v_max_f32_e32 v182, 0x1e3ce508, v182
	v_max_f32_e32 v104, 0x1e3ce508, v104
	v_max_f32_e32 v183, 0x1e3ce508, v183
	v_rcp_f32_e32 v99, v99
	v_rcp_f32_e32 v180, v180
	v_rcp_f32_e32 v100, v100
	v_rcp_f32_e32 v181, v181
	v_rcp_f32_e32 v103, v103
	v_rcp_f32_e32 v182, v182
	v_rcp_f32_e32 v104, v104
	v_rcp_f32_e32 v183, v183
	v_and_b32_e32 v176, 0xffff0000, v176
	v_lshlrev_b32_e32 v98, 16, v177
	v_and_b32_e32 v177, 0xffff0000, v177
	v_lshlrev_b32_e32 v101, 16, v178
	v_and_b32_e32 v178, 0xffff0000, v178
	v_lshlrev_b32_e32 v102, 16, v179
	v_and_b32_e32 v179, 0xffff0000, v179
	v_mov_b32_e32 v105, v180
	v_mov_b32_e32 v106, v181
	v_mov_b32_e32 v107, v182
	v_mov_b32_e32 v108, v183
	v_mul_f32_e32 v180, v99, v93
	v_mul_f32_e32 v181, v105, v176
	v_mul_f32_e32 v182, v100, v98
	v_mul_f32_e32 v183, v106, v177
	v_mul_f32_e32 v176, v103, v101
	v_mul_f32_e32 v177, v107, v178
	v_mul_f32_e32 v178, v104, v102
	v_mul_f32_e32 v179, v108, v179
	v_pk_mul_f32 v[32:33], v[32:33], v[182:183]
	v_pk_mul_f32 v[30:31], v[30:31], v[180:181]
	v_pk_mul_f32 v[28:29], v[28:29], v[178:179]
	v_pk_mul_f32 v[26:27], v[26:27], v[176:177]
	s_cbranch_vccnz .LBB0_1138
	v_lshl_add_u64 v[84:85], v[80:81], 1, v[84:85]
	v_cvt_pk_bf16_f32 v180, v30, v31
	v_cvt_pk_bf16_f32 v181, v32, v33
	v_cvt_pk_bf16_f32 v182, v26, v27
	v_cvt_pk_bf16_f32 v183, v28, v29
	global_store_dwordx4 v[84:85], v[180:183], off offset:256
.LBB0_1138:
	v_add3_u32 v84, v92, s13, 16
	s_nop 0
	v_mov_b64_e32 v[86:87], s[8:9]
	v_mad_i64_i32 v[86:87], s[44:45], v84, s85, v[86:87]
	v_lshl_add_u64 v[88:89], v[86:87], 0, s[88:89]
	s_lshl_b32 s86, s28, 1
	s_mov_b32 s27, s87
	v_lshl_add_u64 v[86:87], v[88:89], 0, s[86:87]
	v_lshl_add_u64 v[88:89], v[88:89], 0, s[26:27]
	v_lshl_add_u64 v[86:87], v[86:87], 0, v[82:83]
	v_lshl_add_u64 v[88:89], v[88:89], 0, v[82:83]
	global_load_dwordx4 v[94:97], v[86:87], off
	global_load_dwordx4 v[98:101], v[88:89], off
	global_load_dwordx4 v[176:179], v[86:87], off offset:256
	global_load_dwordx4 v[180:183], v[88:89], off offset:256
	v_ashrrev_i32_e32 v85, 31, v84
	v_lshlrev_b64 v[84:85], 11, v[84:85]
	s_and_b64 vcc, exec, s[4:5]
	v_lshl_add_u64 v[84:85], s[10:11], 0, v[84:85]
	s_waitcnt vmcnt(2)
	v_lshlrev_b32_e32 v93, 16, v94
	v_and_b32_e32 v102, 0xffff0000, v94
	v_lshlrev_b32_e32 v103, 16, v95
	v_and_b32_e32 v104, 0xffff0000, v95
	v_lshlrev_b32_e32 v94, 16, v98
	v_and_b32_e32 v95, 0xffff0000, v98
	v_lshlrev_b32_e32 v98, 16, v99
	v_and_b32_e32 v99, 0xffff0000, v99
	v_lshlrev_b32_e32 v105, 16, v96
	v_and_b32_e32 v106, 0xffff0000, v96
	v_lshlrev_b32_e32 v107, 16, v97
	v_and_b32_e32 v108, 0xffff0000, v97
	v_lshlrev_b32_e32 v96, 16, v100
	v_and_b32_e32 v97, 0xffff0000, v100
	v_lshlrev_b32_e32 v100, 16, v101
	v_and_b32_e32 v101, 0xffff0000, v101
	v_max_f32_e32 v94, 0x1e3ce508, v94
	v_max_f32_e32 v95, 0x1e3ce508, v95
	v_max_f32_e32 v98, 0x1e3ce508, v98
	v_max_f32_e32 v99, 0x1e3ce508, v99
	v_max_f32_e32 v96, 0x1e3ce508, v96
	v_max_f32_e32 v97, 0x1e3ce508, v97
	v_max_f32_e32 v100, 0x1e3ce508, v100
	v_max_f32_e32 v101, 0x1e3ce508, v101
	v_rcp_f32_e32 v94, v94
	v_rcp_f32_e32 v95, v95
	v_rcp_f32_e32 v98, v98
	v_rcp_f32_e32 v99, v99
	v_rcp_f32_e32 v96, v96
	v_rcp_f32_e32 v97, v97
	v_rcp_f32_e32 v100, v100
	v_rcp_f32_e32 v101, v101
	v_mov_b32_e32 v109, v96
	v_mov_b32_e32 v110, v97
	v_mul_f32_e32 v94, v94, v93
	v_mul_f32_e32 v95, v95, v102
	v_mul_f32_e32 v96, v98, v103
	v_mul_f32_e32 v97, v99, v104
	v_mul_f32_e32 v98, v109, v105
	v_mul_f32_e32 v99, v110, v106
	v_mul_f32_e32 v100, v100, v107
	v_mul_f32_e32 v101, v101, v108
	v_pk_mul_f32 v[56:57], v[56:57], v[96:97]
	v_pk_mul_f32 v[54:55], v[54:55], v[94:95]
	v_pk_mul_f32 v[52:53], v[52:53], v[100:101]
	v_pk_mul_f32 v[50:51], v[50:51], v[98:99]
	s_waitcnt vmcnt(0)
	s_cbranch_vccnz .LBB0_1140
	v_lshl_add_u64 v[98:99], v[80:81], 1, v[84:85]
	v_cvt_pk_bf16_f32 v94, v54, v55
	v_cvt_pk_bf16_f32 v95, v56, v57
	v_cvt_pk_bf16_f32 v96, v50, v51
	v_cvt_pk_bf16_f32 v97, v52, v53
	global_store_dwordx4 v[98:99], v[94:97], off
.LBB0_1140:
	s_and_b64 vcc, exec, s[4:5]
	v_lshlrev_b32_e32 v93, 16, v176
	v_lshlrev_b32_e32 v99, 16, v180
	v_and_b32_e32 v180, 0xffff0000, v180
	v_lshlrev_b32_e32 v100, 16, v181
	v_and_b32_e32 v181, 0xffff0000, v181
	v_lshlrev_b32_e32 v103, 16, v182
	v_and_b32_e32 v182, 0xffff0000, v182
	v_lshlrev_b32_e32 v104, 16, v183
	v_and_b32_e32 v183, 0xffff0000, v183
	v_max_f32_e32 v99, 0x1e3ce508, v99
	v_max_f32_e32 v180, 0x1e3ce508, v180
	v_max_f32_e32 v100, 0x1e3ce508, v100
	v_max_f32_e32 v181, 0x1e3ce508, v181
	v_max_f32_e32 v103, 0x1e3ce508, v103
	v_max_f32_e32 v182, 0x1e3ce508, v182
	v_max_f32_e32 v104, 0x1e3ce508, v104
	v_max_f32_e32 v183, 0x1e3ce508, v183
	v_rcp_f32_e32 v99, v99
	v_rcp_f32_e32 v180, v180
	v_rcp_f32_e32 v100, v100
	v_rcp_f32_e32 v181, v181
	v_rcp_f32_e32 v103, v103
	v_rcp_f32_e32 v182, v182
	v_rcp_f32_e32 v104, v104
	v_rcp_f32_e32 v183, v183
	v_and_b32_e32 v176, 0xffff0000, v176
	v_lshlrev_b32_e32 v98, 16, v177
	v_and_b32_e32 v177, 0xffff0000, v177
	v_lshlrev_b32_e32 v101, 16, v178
	v_and_b32_e32 v178, 0xffff0000, v178
	v_lshlrev_b32_e32 v102, 16, v179
	v_and_b32_e32 v179, 0xffff0000, v179
	v_mov_b32_e32 v105, v180
	v_mov_b32_e32 v106, v181
	v_mov_b32_e32 v107, v182
	v_mov_b32_e32 v108, v183
	v_mul_f32_e32 v180, v99, v93
	v_mul_f32_e32 v181, v105, v176
	v_mul_f32_e32 v182, v100, v98
	v_mul_f32_e32 v183, v106, v177
	v_mul_f32_e32 v176, v103, v101
	v_mul_f32_e32 v177, v107, v178
	v_mul_f32_e32 v178, v104, v102
	v_mul_f32_e32 v179, v108, v179
	v_pk_mul_f32 v[24:25], v[24:25], v[182:183]
	v_pk_mul_f32 v[22:23], v[22:23], v[180:181]
	v_pk_mul_f32 v[20:21], v[20:21], v[178:179]
	v_pk_mul_f32 v[18:19], v[18:19], v[176:177]
	s_cbranch_vccnz .LBB0_1142
	v_lshl_add_u64 v[84:85], v[80:81], 1, v[84:85]
	v_cvt_pk_bf16_f32 v180, v22, v23
	v_cvt_pk_bf16_f32 v181, v24, v25
	v_cvt_pk_bf16_f32 v182, v18, v19
	v_cvt_pk_bf16_f32 v183, v20, v21
	global_store_dwordx4 v[84:85], v[180:183], off offset:256
.LBB0_1142:
	v_add3_u32 v84, v92, s13, 32
	s_nop 0
	v_mov_b64_e32 v[86:87], s[8:9]
	v_mad_i64_i32 v[86:87], s[28:29], v84, s85, v[86:87]
	v_lshl_add_u64 v[88:89], v[86:87], 0, s[88:89]
	s_mov_b32 s27, s87
	v_lshl_add_u64 v[86:87], v[88:89], 0, s[86:87]
	v_lshl_add_u64 v[88:89], v[88:89], 0, s[26:27]
	v_lshl_add_u64 v[86:87], v[86:87], 0, v[82:83]
	v_lshl_add_u64 v[88:89], v[88:89], 0, v[82:83]
	global_load_dwordx4 v[94:97], v[86:87], off
	global_load_dwordx4 v[98:101], v[88:89], off
	global_load_dwordx4 v[176:179], v[86:87], off offset:256
	global_load_dwordx4 v[180:183], v[88:89], off offset:256
	v_ashrrev_i32_e32 v85, 31, v84
	v_lshlrev_b64 v[84:85], 11, v[84:85]
	s_and_b64 vcc, exec, s[4:5]
	v_lshl_add_u64 v[84:85], s[10:11], 0, v[84:85]
	s_waitcnt vmcnt(2)
	v_lshlrev_b32_e32 v93, 16, v94
	v_and_b32_e32 v102, 0xffff0000, v94
	v_lshlrev_b32_e32 v103, 16, v95
	v_and_b32_e32 v104, 0xffff0000, v95
	v_lshlrev_b32_e32 v94, 16, v98
	v_and_b32_e32 v95, 0xffff0000, v98
	v_lshlrev_b32_e32 v98, 16, v99
	v_and_b32_e32 v99, 0xffff0000, v99
	v_lshlrev_b32_e32 v105, 16, v96
	v_and_b32_e32 v106, 0xffff0000, v96
	v_lshlrev_b32_e32 v107, 16, v97
	v_and_b32_e32 v108, 0xffff0000, v97
	v_lshlrev_b32_e32 v96, 16, v100
	v_and_b32_e32 v97, 0xffff0000, v100
	v_lshlrev_b32_e32 v100, 16, v101
	v_and_b32_e32 v101, 0xffff0000, v101
	v_max_f32_e32 v94, 0x1e3ce508, v94
	v_max_f32_e32 v95, 0x1e3ce508, v95
	v_max_f32_e32 v98, 0x1e3ce508, v98
	v_max_f32_e32 v99, 0x1e3ce508, v99
	v_max_f32_e32 v96, 0x1e3ce508, v96
	v_max_f32_e32 v97, 0x1e3ce508, v97
	v_max_f32_e32 v100, 0x1e3ce508, v100
	v_max_f32_e32 v101, 0x1e3ce508, v101
	v_rcp_f32_e32 v94, v94
	v_rcp_f32_e32 v95, v95
	v_rcp_f32_e32 v98, v98
	v_rcp_f32_e32 v99, v99
	v_rcp_f32_e32 v96, v96
	v_rcp_f32_e32 v97, v97
	v_rcp_f32_e32 v100, v100
	v_rcp_f32_e32 v101, v101
	v_mov_b32_e32 v109, v96
	v_mov_b32_e32 v110, v97
	v_mul_f32_e32 v94, v94, v93
	v_mul_f32_e32 v95, v95, v102
	v_mul_f32_e32 v96, v98, v103
	v_mul_f32_e32 v97, v99, v104
	v_mul_f32_e32 v98, v109, v105
	v_mul_f32_e32 v99, v110, v106
	v_mul_f32_e32 v100, v100, v107
	v_mul_f32_e32 v101, v101, v108
	v_pk_mul_f32 v[48:49], v[48:49], v[96:97]
	v_pk_mul_f32 v[46:47], v[46:47], v[94:95]
	v_pk_mul_f32 v[44:45], v[44:45], v[100:101]
	v_pk_mul_f32 v[42:43], v[42:43], v[98:99]
	s_waitcnt vmcnt(0)
	s_cbranch_vccnz .LBB0_1144
	v_lshl_add_u64 v[98:99], v[80:81], 1, v[84:85]
	v_cvt_pk_bf16_f32 v94, v46, v47
	v_cvt_pk_bf16_f32 v95, v48, v49
	v_cvt_pk_bf16_f32 v96, v42, v43
	v_cvt_pk_bf16_f32 v97, v44, v45
	global_store_dwordx4 v[98:99], v[94:97], off
.LBB0_1144:
	s_and_b64 vcc, exec, s[4:5]
	v_lshlrev_b32_e32 v93, 16, v176
	v_lshlrev_b32_e32 v99, 16, v180
	v_and_b32_e32 v180, 0xffff0000, v180
	v_lshlrev_b32_e32 v100, 16, v181
	v_and_b32_e32 v181, 0xffff0000, v181
	v_lshlrev_b32_e32 v103, 16, v182
	v_and_b32_e32 v182, 0xffff0000, v182
	v_lshlrev_b32_e32 v104, 16, v183
	v_and_b32_e32 v183, 0xffff0000, v183
	v_max_f32_e32 v99, 0x1e3ce508, v99
	v_max_f32_e32 v180, 0x1e3ce508, v180
	v_max_f32_e32 v100, 0x1e3ce508, v100
	v_max_f32_e32 v181, 0x1e3ce508, v181
	v_max_f32_e32 v103, 0x1e3ce508, v103
	v_max_f32_e32 v182, 0x1e3ce508, v182
	v_max_f32_e32 v104, 0x1e3ce508, v104
	v_max_f32_e32 v183, 0x1e3ce508, v183
	v_rcp_f32_e32 v99, v99
	v_rcp_f32_e32 v180, v180
	v_rcp_f32_e32 v100, v100
	v_rcp_f32_e32 v181, v181
	v_rcp_f32_e32 v103, v103
	v_rcp_f32_e32 v182, v182
	v_rcp_f32_e32 v104, v104
	v_rcp_f32_e32 v183, v183
	v_and_b32_e32 v176, 0xffff0000, v176
	v_lshlrev_b32_e32 v98, 16, v177
	v_and_b32_e32 v177, 0xffff0000, v177
	v_lshlrev_b32_e32 v101, 16, v178
	v_and_b32_e32 v178, 0xffff0000, v178
	v_lshlrev_b32_e32 v102, 16, v179
	v_and_b32_e32 v179, 0xffff0000, v179
	v_mov_b32_e32 v105, v180
	v_mov_b32_e32 v106, v181
	v_mov_b32_e32 v107, v182
	v_mov_b32_e32 v108, v183
	v_mul_f32_e32 v180, v99, v93
	v_mul_f32_e32 v181, v105, v176
	v_mul_f32_e32 v182, v100, v98
	v_mul_f32_e32 v183, v106, v177
	v_mul_f32_e32 v176, v103, v101
	v_mul_f32_e32 v177, v107, v178
	v_mul_f32_e32 v178, v104, v102
	v_mul_f32_e32 v179, v108, v179
	v_pk_mul_f32 v[16:17], v[16:17], v[182:183]
	v_pk_mul_f32 v[14:15], v[14:15], v[180:181]
	v_pk_mul_f32 v[12:13], v[12:13], v[178:179]
	v_pk_mul_f32 v[10:11], v[10:11], v[176:177]
	s_cbranch_vccnz .LBB0_1146
	v_lshl_add_u64 v[84:85], v[80:81], 1, v[84:85]
	v_cvt_pk_bf16_f32 v180, v14, v15
	v_cvt_pk_bf16_f32 v181, v16, v17
	v_cvt_pk_bf16_f32 v182, v10, v11
	v_cvt_pk_bf16_f32 v183, v12, v13
	global_store_dwordx4 v[84:85], v[180:183], off offset:256
.LBB0_1146:
	s_nop 1
	v_add3_u32 v88, v92, s13, 48
	v_mov_b64_e32 v[84:85], s[8:9]
	v_mad_i64_i32 v[84:85], s[28:29], v88, s85, v[84:85]
	v_lshl_add_u64 v[86:87], v[84:85], 0, s[88:89]
	s_mov_b32 s27, s87
	v_lshl_add_u64 v[84:85], v[86:87], 0, s[86:87]
	v_lshl_add_u64 v[86:87], v[86:87], 0, s[26:27]
	v_lshl_add_u64 v[84:85], v[84:85], 0, v[82:83]
	v_lshl_add_u64 v[86:87], v[86:87], 0, v[82:83]
	global_load_dwordx4 v[92:95], v[84:85], off
	global_load_dwordx4 v[96:99], v[86:87], off
	global_load_dwordx4 v[176:179], v[84:85], off offset:256
	global_load_dwordx4 v[180:183], v[86:87], off offset:256
	v_ashrrev_i32_e32 v89, 31, v88
	v_lshlrev_b64 v[82:83], 11, v[88:89]
	s_and_b64 vcc, exec, s[4:5]
	v_lshl_add_u64 v[82:83], s[10:11], 0, v[82:83]
	s_waitcnt vmcnt(2)
	v_lshlrev_b32_e32 v102, 16, v94
	v_lshlrev_b32_e32 v100, 16, v96
	v_and_b32_e32 v96, 0xffff0000, v96
	v_lshlrev_b32_e32 v101, 16, v97
	v_and_b32_e32 v97, 0xffff0000, v97
	v_and_b32_e32 v103, 0xffff0000, v94
	v_lshlrev_b32_e32 v104, 16, v95
	v_and_b32_e32 v105, 0xffff0000, v95
	v_lshlrev_b32_e32 v94, 16, v98
	v_and_b32_e32 v95, 0xffff0000, v98
	v_lshlrev_b32_e32 v98, 16, v99
	v_and_b32_e32 v99, 0xffff0000, v99
	v_max_f32_e32 v100, 0x1e3ce508, v100
	v_max_f32_e32 v96, 0x1e3ce508, v96
	v_max_f32_e32 v101, 0x1e3ce508, v101
	v_max_f32_e32 v97, 0x1e3ce508, v97
	v_max_f32_e32 v94, 0x1e3ce508, v94
	v_max_f32_e32 v95, 0x1e3ce508, v95
	v_max_f32_e32 v98, 0x1e3ce508, v98
	v_max_f32_e32 v99, 0x1e3ce508, v99
	v_rcp_f32_e32 v100, v100
	v_rcp_f32_e32 v96, v96
	v_rcp_f32_e32 v101, v101
	v_rcp_f32_e32 v97, v97
	v_rcp_f32_e32 v94, v94
	v_rcp_f32_e32 v95, v95
	v_rcp_f32_e32 v98, v98
	v_rcp_f32_e32 v99, v99
	v_lshlrev_b32_e32 v88, 16, v92
	v_and_b32_e32 v89, 0xffff0000, v92
	v_lshlrev_b32_e32 v92, 16, v93
	v_and_b32_e32 v93, 0xffff0000, v93
	v_mul_f32_e32 v88, v100, v88
	v_mul_f32_e32 v89, v96, v89
	v_mul_f32_e32 v92, v101, v92
	v_mul_f32_e32 v93, v97, v93
	v_mul_f32_e32 v94, v94, v102
	v_mul_f32_e32 v95, v95, v103
	v_mul_f32_e32 v96, v98, v104
	v_mul_f32_e32 v97, v99, v105
	v_pk_mul_f32 v[40:41], v[40:41], v[92:93]
	v_pk_mul_f32 v[38:39], v[38:39], v[88:89]
	v_pk_mul_f32 v[36:37], v[36:37], v[96:97]
	v_pk_mul_f32 v[34:35], v[34:35], v[94:95]
	s_waitcnt vmcnt(0)
	s_cbranch_vccnz .LBB0_1148
	v_lshl_add_u64 v[88:89], v[80:81], 1, v[82:83]
	v_cvt_pk_bf16_f32 v92, v38, v39
	v_cvt_pk_bf16_f32 v93, v40, v41
	v_cvt_pk_bf16_f32 v94, v34, v35
	v_cvt_pk_bf16_f32 v95, v36, v37
	global_store_dwordx4 v[88:89], v[92:95], off
.LBB0_1148:
	s_and_b64 vcc, exec, s[4:5]
	v_lshlrev_b32_e32 v88, 16, v176
	v_lshlrev_b32_e32 v96, 16, v180
	v_and_b32_e32 v180, 0xffff0000, v180
	v_lshlrev_b32_e32 v97, 16, v181
	v_and_b32_e32 v181, 0xffff0000, v181
	v_lshlrev_b32_e32 v100, 16, v182
	v_and_b32_e32 v182, 0xffff0000, v182
	v_lshlrev_b32_e32 v101, 16, v183
	v_and_b32_e32 v183, 0xffff0000, v183
	v_max_f32_e32 v96, 0x1e3ce508, v96
	v_max_f32_e32 v180, 0x1e3ce508, v180
	v_max_f32_e32 v97, 0x1e3ce508, v97
	v_max_f32_e32 v181, 0x1e3ce508, v181
	v_max_f32_e32 v100, 0x1e3ce508, v100
	v_max_f32_e32 v182, 0x1e3ce508, v182
	v_max_f32_e32 v101, 0x1e3ce508, v101
	v_max_f32_e32 v183, 0x1e3ce508, v183
	v_rcp_f32_e32 v96, v96
	v_rcp_f32_e32 v180, v180
	v_rcp_f32_e32 v97, v97
	v_rcp_f32_e32 v181, v181
	v_rcp_f32_e32 v100, v100
	v_rcp_f32_e32 v182, v182
	v_rcp_f32_e32 v101, v101
	v_rcp_f32_e32 v183, v183
	v_and_b32_e32 v89, 0xffff0000, v176
	v_lshlrev_b32_e32 v176, 16, v177
	v_and_b32_e32 v177, 0xffff0000, v177
	v_lshlrev_b32_e32 v98, 16, v178
	v_and_b32_e32 v178, 0xffff0000, v178
	v_lshlrev_b32_e32 v99, 16, v179
	v_and_b32_e32 v179, 0xffff0000, v179
	v_mov_b32_e32 v102, v180
	v_mov_b32_e32 v103, v181
	v_mov_b32_e32 v104, v182
	v_mov_b32_e32 v105, v183
	v_mul_f32_e32 v180, v96, v88
	v_mul_f32_e32 v181, v102, v89
	v_mul_f32_e32 v182, v97, v176
	v_mul_f32_e32 v183, v103, v177
	v_mul_f32_e32 v88, v100, v98
	v_mul_f32_e32 v89, v104, v178
	v_mul_f32_e32 v176, v101, v99
	v_mul_f32_e32 v177, v105, v179
	v_pk_mul_f32 v[8:9], v[8:9], v[182:183]
	v_pk_mul_f32 v[6:7], v[6:7], v[180:181]
	v_pk_mul_f32 v[4:5], v[4:5], v[176:177]
	v_pk_mul_f32 v[2:3], v[2:3], v[88:89]
	s_cbranch_vccnz .LBB0_1150
	v_lshl_add_u64 v[80:81], v[80:81], 1, v[82:83]
	v_cvt_pk_bf16_f32 v180, v6, v7
	v_cvt_pk_bf16_f32 v181, v8, v9
	v_cvt_pk_bf16_f32 v182, v2, v3
	v_cvt_pk_bf16_f32 v183, v4, v5
	global_store_dwordx4 v[80:81], v[180:183], off offset:256
	s_branch .LBB0_1150
.Lmrg_fin_B:
	global_load_dwordx4 v[94:97], v[86:87], off
	global_load_dwordx4 v[98:101], v[88:89], off
	global_load_dwordx4 v[176:179], v[86:87], off offset:256
	global_load_dwordx4 v[180:183], v[88:89], off offset:256
	v_ashrrev_i32_e32 v85, 31, v84
	v_lshlrev_b64 v[84:85], 11, v[84:85]
	s_cmp_lg_u32 s43, 2
	v_lshl_add_u64 v[84:85], s[10:11], 0, v[84:85]
	s_waitcnt vmcnt(2)
	v_lshlrev_b32_e32 v93, 16, v94
	v_and_b32_e32 v102, 0xffff0000, v94
	v_lshlrev_b32_e32 v103, 16, v95
	v_and_b32_e32 v104, 0xffff0000, v95
	v_lshlrev_b32_e32 v105, 16, v96
	v_and_b32_e32 v106, 0xffff0000, v96
	v_lshlrev_b32_e32 v107, 16, v97
	v_and_b32_e32 v108, 0xffff0000, v97
	v_mov_b32_e32 v94, v93
	v_mov_b32_e32 v95, v102
	v_mov_b32_e32 v96, v103
	v_mov_b32_e32 v97, v104
	v_mov_b32_e32 v98, v105
	v_mov_b32_e32 v99, v106
	v_mov_b32_e32 v100, v107
	v_mov_b32_e32 v101, v108
	v_pk_mul_f32 v[64:65], v[64:65], v[96:97]
	v_pk_mul_f32 v[62:63], v[62:63], v[94:95]
	v_pk_mul_f32 v[60:61], v[60:61], v[100:101]
	v_pk_mul_f32 v[58:59], v[58:59], v[98:99]
	s_waitcnt vmcnt(0)
	s_cbranch_scc1 .LBB0_1136_B
	v_lshl_add_u64 v[98:99], v[80:81], 1, v[84:85]
	v_cvt_pk_bf16_f32 v94, v62, v63
	v_cvt_pk_bf16_f32 v95, v64, v65
	v_cvt_pk_bf16_f32 v96, v58, v59
	v_cvt_pk_bf16_f32 v97, v60, v61
	global_store_dwordx4 v[98:99], v[94:97], off
.LBB0_1136_B:
	v_cndmask_b32_e64 v93, 0, 1, s[20:21]
	v_cmp_ne_u32_e64 s[4:5], 1, v93
	s_andn2_b64 vcc, exec, s[20:21]
	v_lshlrev_b32_e32 v93, 16, v176
	v_and_b32_e32 v176, 0xffff0000, v176
	v_lshlrev_b32_e32 v98, 16, v177
	v_and_b32_e32 v177, 0xffff0000, v177
	v_lshlrev_b32_e32 v101, 16, v178
	v_and_b32_e32 v178, 0xffff0000, v178
	v_lshlrev_b32_e32 v102, 16, v179
	v_and_b32_e32 v179, 0xffff0000, v179
	v_mov_b32_e32 v180, v93
	v_mov_b32_e32 v181, v176
	v_mov_b32_e32 v182, v98
	v_mov_b32_e32 v183, v177
	v_mov_b32_e32 v176, v101
	v_mov_b32_e32 v177, v178
	v_mov_b32_e32 v178, v102
	v_mov_b32_e32 v179, v179
	v_pk_mul_f32 v[32:33], v[32:33], v[182:183]
	v_pk_mul_f32 v[30:31], v[30:31], v[180:181]
	v_pk_mul_f32 v[28:29], v[28:29], v[178:179]
	v_pk_mul_f32 v[26:27], v[26:27], v[176:177]
	s_cbranch_vccnz .LBB0_1138_B
	v_lshl_add_u64 v[84:85], v[80:81], 1, v[84:85]
	v_cvt_pk_bf16_f32 v180, v30, v31
	v_cvt_pk_bf16_f32 v181, v32, v33
	v_cvt_pk_bf16_f32 v182, v26, v27
	v_cvt_pk_bf16_f32 v183, v28, v29
	global_store_dwordx4 v[84:85], v[180:183], off offset:256
.LBB0_1138_B:
	v_add3_u32 v84, v92, s13, 16
	s_nop 0
	v_mov_b64_e32 v[86:87], s[8:9]
	v_mad_i64_i32 v[86:87], s[44:45], v84, s85, v[86:87]
	v_lshl_add_u64 v[88:89], v[86:87], 0, s[88:89]
	s_lshl_b32 s86, s28, 1
	s_mov_b32 s27, s87
	v_lshl_add_u64 v[86:87], v[88:89], 0, s[86:87]
	v_lshl_add_u64 v[88:89], v[88:89], 0, s[26:27]
	v_lshl_add_u64 v[86:87], v[86:87], 0, v[82:83]
	v_lshl_add_u64 v[88:89], v[88:89], 0, v[82:83]
	global_load_dwordx4 v[94:97], v[86:87], off
	global_load_dwordx4 v[98:101], v[88:89], off
	global_load_dwordx4 v[176:179], v[86:87], off offset:256
	global_load_dwordx4 v[180:183], v[88:89], off offset:256
	v_ashrrev_i32_e32 v85, 31, v84
	v_lshlrev_b64 v[84:85], 11, v[84:85]
	s_and_b64 vcc, exec, s[4:5]
	v_lshl_add_u64 v[84:85], s[10:11], 0, v[84:85]
	s_waitcnt vmcnt(2)
	v_lshlrev_b32_e32 v93, 16, v94
	v_and_b32_e32 v102, 0xffff0000, v94
	v_lshlrev_b32_e32 v103, 16, v95
	v_and_b32_e32 v104, 0xffff0000, v95
	v_lshlrev_b32_e32 v105, 16, v96
	v_and_b32_e32 v106, 0xffff0000, v96
	v_lshlrev_b32_e32 v107, 16, v97
	v_and_b32_e32 v108, 0xffff0000, v97
	v_mov_b32_e32 v94, v93
	v_mov_b32_e32 v95, v102
	v_mov_b32_e32 v96, v103
	v_mov_b32_e32 v97, v104
	v_mov_b32_e32 v98, v105
	v_mov_b32_e32 v99, v106
	v_mov_b32_e32 v100, v107
	v_mov_b32_e32 v101, v108
	v_pk_mul_f32 v[56:57], v[56:57], v[96:97]
	v_pk_mul_f32 v[54:55], v[54:55], v[94:95]
	v_pk_mul_f32 v[52:53], v[52:53], v[100:101]
	v_pk_mul_f32 v[50:51], v[50:51], v[98:99]
	s_waitcnt vmcnt(0)
	s_cbranch_vccnz .LBB0_1140_B
	v_lshl_add_u64 v[98:99], v[80:81], 1, v[84:85]
	v_cvt_pk_bf16_f32 v94, v54, v55
	v_cvt_pk_bf16_f32 v95, v56, v57
	v_cvt_pk_bf16_f32 v96, v50, v51
	v_cvt_pk_bf16_f32 v97, v52, v53
	global_store_dwordx4 v[98:99], v[94:97], off
.LBB0_1140_B:
	s_and_b64 vcc, exec, s[4:5]
	v_lshlrev_b32_e32 v93, 16, v176
	v_and_b32_e32 v176, 0xffff0000, v176
	v_lshlrev_b32_e32 v98, 16, v177
	v_and_b32_e32 v177, 0xffff0000, v177
	v_lshlrev_b32_e32 v101, 16, v178
	v_and_b32_e32 v178, 0xffff0000, v178
	v_lshlrev_b32_e32 v102, 16, v179
	v_and_b32_e32 v179, 0xffff0000, v179
	v_mov_b32_e32 v180, v93
	v_mov_b32_e32 v181, v176
	v_mov_b32_e32 v182, v98
	v_mov_b32_e32 v183, v177
	v_mov_b32_e32 v176, v101
	v_mov_b32_e32 v177, v178
	v_mov_b32_e32 v178, v102
	v_mov_b32_e32 v179, v179
	v_pk_mul_f32 v[24:25], v[24:25], v[182:183]
	v_pk_mul_f32 v[22:23], v[22:23], v[180:181]
	v_pk_mul_f32 v[20:21], v[20:21], v[178:179]
	v_pk_mul_f32 v[18:19], v[18:19], v[176:177]
	s_cbranch_vccnz .LBB0_1142_B
	v_lshl_add_u64 v[84:85], v[80:81], 1, v[84:85]
	v_cvt_pk_bf16_f32 v180, v22, v23
	v_cvt_pk_bf16_f32 v181, v24, v25
	v_cvt_pk_bf16_f32 v182, v18, v19
	v_cvt_pk_bf16_f32 v183, v20, v21
	global_store_dwordx4 v[84:85], v[180:183], off offset:256
.LBB0_1142_B:
	v_add3_u32 v84, v92, s13, 32
	s_nop 0
	v_mov_b64_e32 v[86:87], s[8:9]
	v_mad_i64_i32 v[86:87], s[28:29], v84, s85, v[86:87]
	v_lshl_add_u64 v[88:89], v[86:87], 0, s[88:89]
	s_mov_b32 s27, s87
	v_lshl_add_u64 v[86:87], v[88:89], 0, s[86:87]
	v_lshl_add_u64 v[88:89], v[88:89], 0, s[26:27]
	v_lshl_add_u64 v[86:87], v[86:87], 0, v[82:83]
	v_lshl_add_u64 v[88:89], v[88:89], 0, v[82:83]
	global_load_dwordx4 v[94:97], v[86:87], off
	global_load_dwordx4 v[98:101], v[88:89], off
	global_load_dwordx4 v[176:179], v[86:87], off offset:256
	global_load_dwordx4 v[180:183], v[88:89], off offset:256
	v_ashrrev_i32_e32 v85, 31, v84
	v_lshlrev_b64 v[84:85], 11, v[84:85]
	s_and_b64 vcc, exec, s[4:5]
	v_lshl_add_u64 v[84:85], s[10:11], 0, v[84:85]
	s_waitcnt vmcnt(2)
	v_lshlrev_b32_e32 v93, 16, v94
	v_and_b32_e32 v102, 0xffff0000, v94
	v_lshlrev_b32_e32 v103, 16, v95
	v_and_b32_e32 v104, 0xffff0000, v95
	v_lshlrev_b32_e32 v105, 16, v96
	v_and_b32_e32 v106, 0xffff0000, v96
	v_lshlrev_b32_e32 v107, 16, v97
	v_and_b32_e32 v108, 0xffff0000, v97
	v_mov_b32_e32 v94, v93
	v_mov_b32_e32 v95, v102
	v_mov_b32_e32 v96, v103
	v_mov_b32_e32 v97, v104
	v_mov_b32_e32 v98, v105
	v_mov_b32_e32 v99, v106
	v_mov_b32_e32 v100, v107
	v_mov_b32_e32 v101, v108
	v_pk_mul_f32 v[48:49], v[48:49], v[96:97]
	v_pk_mul_f32 v[46:47], v[46:47], v[94:95]
	v_pk_mul_f32 v[44:45], v[44:45], v[100:101]
	v_pk_mul_f32 v[42:43], v[42:43], v[98:99]
	s_waitcnt vmcnt(0)
	s_cbranch_vccnz .LBB0_1144_B
	v_lshl_add_u64 v[98:99], v[80:81], 1, v[84:85]
	v_cvt_pk_bf16_f32 v94, v46, v47
	v_cvt_pk_bf16_f32 v95, v48, v49
	v_cvt_pk_bf16_f32 v96, v42, v43
	v_cvt_pk_bf16_f32 v97, v44, v45
	global_store_dwordx4 v[98:99], v[94:97], off
.LBB0_1144_B:
	s_and_b64 vcc, exec, s[4:5]
	v_lshlrev_b32_e32 v93, 16, v176
	v_and_b32_e32 v176, 0xffff0000, v176
	v_lshlrev_b32_e32 v98, 16, v177
	v_and_b32_e32 v177, 0xffff0000, v177
	v_lshlrev_b32_e32 v101, 16, v178
	v_and_b32_e32 v178, 0xffff0000, v178
	v_lshlrev_b32_e32 v102, 16, v179
	v_and_b32_e32 v179, 0xffff0000, v179
	v_mov_b32_e32 v180, v93
	v_mov_b32_e32 v181, v176
	v_mov_b32_e32 v182, v98
	v_mov_b32_e32 v183, v177
	v_mov_b32_e32 v176, v101
	v_mov_b32_e32 v177, v178
	v_mov_b32_e32 v178, v102
	v_mov_b32_e32 v179, v179
	v_pk_mul_f32 v[16:17], v[16:17], v[182:183]
	v_pk_mul_f32 v[14:15], v[14:15], v[180:181]
	v_pk_mul_f32 v[12:13], v[12:13], v[178:179]
	v_pk_mul_f32 v[10:11], v[10:11], v[176:177]
	s_cbranch_vccnz .LBB0_1146_B
	v_lshl_add_u64 v[84:85], v[80:81], 1, v[84:85]
	v_cvt_pk_bf16_f32 v180, v14, v15
	v_cvt_pk_bf16_f32 v181, v16, v17
	v_cvt_pk_bf16_f32 v182, v10, v11
	v_cvt_pk_bf16_f32 v183, v12, v13
	global_store_dwordx4 v[84:85], v[180:183], off offset:256
.LBB0_1146_B:
	s_nop 1
	v_add3_u32 v88, v92, s13, 48
	v_mov_b64_e32 v[84:85], s[8:9]
	v_mad_i64_i32 v[84:85], s[28:29], v88, s85, v[84:85]
	v_lshl_add_u64 v[86:87], v[84:85], 0, s[88:89]
	s_mov_b32 s27, s87
	v_lshl_add_u64 v[84:85], v[86:87], 0, s[86:87]
	v_lshl_add_u64 v[86:87], v[86:87], 0, s[26:27]
	v_lshl_add_u64 v[84:85], v[84:85], 0, v[82:83]
	v_lshl_add_u64 v[86:87], v[86:87], 0, v[82:83]
	global_load_dwordx4 v[92:95], v[84:85], off
	global_load_dwordx4 v[96:99], v[86:87], off
	global_load_dwordx4 v[176:179], v[84:85], off offset:256
	global_load_dwordx4 v[180:183], v[86:87], off offset:256
	v_ashrrev_i32_e32 v89, 31, v88
	v_lshlrev_b64 v[82:83], 11, v[88:89]
	s_and_b64 vcc, exec, s[4:5]
	v_lshl_add_u64 v[82:83], s[10:11], 0, v[82:83]
	s_waitcnt vmcnt(2)
	v_lshlrev_b32_e32 v102, 16, v94
	v_and_b32_e32 v103, 0xffff0000, v94
	v_lshlrev_b32_e32 v104, 16, v95
	v_and_b32_e32 v105, 0xffff0000, v95
	v_lshlrev_b32_e32 v88, 16, v92
	v_and_b32_e32 v89, 0xffff0000, v92
	v_lshlrev_b32_e32 v92, 16, v93
	v_and_b32_e32 v93, 0xffff0000, v93
	v_mov_b32_e32 v88, v88
	v_mov_b32_e32 v89, v89
	v_mov_b32_e32 v92, v92
	v_mov_b32_e32 v93, v93
	v_mov_b32_e32 v94, v102
	v_mov_b32_e32 v95, v103
	v_mov_b32_e32 v96, v104
	v_mov_b32_e32 v97, v105
	v_pk_mul_f32 v[40:41], v[40:41], v[92:93]
	v_pk_mul_f32 v[38:39], v[38:39], v[88:89]
	v_pk_mul_f32 v[36:37], v[36:37], v[96:97]
	v_pk_mul_f32 v[34:35], v[34:35], v[94:95]
	s_waitcnt vmcnt(0)
	s_cbranch_vccnz .LBB0_1148_B
	v_lshl_add_u64 v[88:89], v[80:81], 1, v[82:83]
	v_cvt_pk_bf16_f32 v92, v38, v39
	v_cvt_pk_bf16_f32 v93, v40, v41
	v_cvt_pk_bf16_f32 v94, v34, v35
	v_cvt_pk_bf16_f32 v95, v36, v37
	global_store_dwordx4 v[88:89], v[92:95], off
.LBB0_1148_B:
	s_and_b64 vcc, exec, s[4:5]
	v_lshlrev_b32_e32 v88, 16, v176
	v_and_b32_e32 v89, 0xffff0000, v176
	v_lshlrev_b32_e32 v176, 16, v177
	v_and_b32_e32 v177, 0xffff0000, v177
	v_lshlrev_b32_e32 v98, 16, v178
	v_and_b32_e32 v178, 0xffff0000, v178
	v_lshlrev_b32_e32 v99, 16, v179
	v_and_b32_e32 v179, 0xffff0000, v179
	v_mov_b32_e32 v180, v88
	v_mov_b32_e32 v181, v89
	v_mov_b32_e32 v182, v176
	v_mov_b32_e32 v183, v177
	v_mov_b32_e32 v88, v98
	v_mov_b32_e32 v89, v178
	v_mov_b32_e32 v176, v99
	v_mov_b32_e32 v177, v179
	v_pk_mul_f32 v[8:9], v[8:9], v[182:183]
	v_pk_mul_f32 v[6:7], v[6:7], v[180:181]
	v_pk_mul_f32 v[4:5], v[4:5], v[176:177]
	v_pk_mul_f32 v[2:3], v[2:3], v[88:89]
	s_cbranch_vccnz .LBB0_1150
	v_lshl_add_u64 v[80:81], v[80:81], 1, v[82:83]
	v_cvt_pk_bf16_f32 v180, v6, v7
	v_cvt_pk_bf16_f32 v181, v8, v9
	v_cvt_pk_bf16_f32 v182, v2, v3
	v_cvt_pk_bf16_f32 v183, v4, v5
	global_store_dwordx4 v[80:81], v[180:183], off offset:256
